# outer tile-loop headers also aligned to 64 bytes
# speedup vs baseline: 1.0039x; 1.0039x over previous
; __device__ __forceinline__ void prologue_phase(const Params& p, char* smem) {
;     ...
;     for (int task = blockIdx.x; task < ntask; task += gridDim.x) {
;         if (task < NTR) {
.LBB0_27:
	s_add_i32 s48, s48, s58
	v_add_u32_e32 v19, s33, v19
	s_cmpk_lt_i32 s48, 0x18a8
	v_add_u32_e32 v10, s33, v10
	s_cbranch_scc0 .LBB0_97
	.p2alignl 6, 3212836864

; __device__ __forceinline__ u32x4 pack8(f32x4 a, f32x4 b) { u32x4 r; r.x = cvt_pk_bf16(a[0], a[1]); r.y = cvt_pk_bf16(a[2], a[3]); r.z = cvt_pk_bf16(b[0], b[1]); r.w = cvt_pk_bf16(b[2], b[3]); return r; }
; template <class Epi>
; __device__ __forceinline__ void gemm_tile(const bf16_t* __restrict__ A, const bf16_t* __restrict__ Bt, int K, int row0, int col0, const Epi& epi, char* smem,
;                                           bool prefetched, bool nvalid, int nrow0, int ncol0) {
;     ...
;     if constexpr (Epi::STAGED) {
;         bf16_t* st = (bf16_t*)(smem + 2 * TILE_B);
;         epi.to_lds(acc, st, row0, col0, wr, wc, fr, fq);
;         __syncthreads();
;         bf16_t* gbase; size_t gstride;
;         epi.dest(row0, col0, gbase, gstride);
;         const int r0 = tid >> 4, ch = (tid & 15) * 8;
; #pragma unroll
;         for (int it = 0; it < 8; ++it) { const int r = it * 16 + r0; __builtin_nontemporal_store(*(const u32x4*)(st + r * 136 + ch), (u32x4*)(gbase + (size_t)r * gstride + ch)); }
;     __device__ __forceinline__ void to_lds(f32x4 (&acc)[4][4], bf16_t* st, int row0, int col0, int wr, int wc, int fr, int fq) const {
;     ...
;                 if (isq) { v0 = v0 * 0.18033688011112042f; v1 = v1 * 0.18033688011112042f; }
;                 *(u32x4*)(st + rl * 136 + wc * 64 + pp * 32 + 8 * fq) = pack8(v0, v1);
.LBB0_148:
	s_or_b64 exec, exec, s[12:13]
	s_waitcnt lgkmcnt(4)
	v_pk_mul_f32 v[16:17], v[10:11], s[2:3] op_sel_hi:[1,0]
	s_waitcnt vmcnt(1)
	v_pk_mul_f32 v[18:19], v[8:9], s[2:3] op_sel_hi:[1,0]
	v_pk_mul_f32 v[20:21], v[14:15], s[2:3] op_sel_hi:[1,0]
	v_pk_mul_f32 v[22:23], v[12:13], s[2:3] op_sel_hi:[1,0]
	v_cndmask_b32_e32 v15, v15, v21, vcc
	v_cndmask_b32_e32 v14, v14, v20, vcc
	v_cndmask_b32_e32 v13, v13, v23, vcc
	v_cndmask_b32_e32 v12, v12, v22, vcc
	v_cndmask_b32_e32 v11, v11, v17, vcc
	v_cndmask_b32_e32 v10, v10, v16, vcc
	v_cndmask_b32_e32 v9, v9, v19, vcc
	v_cndmask_b32_e32 v8, v8, v18, vcc
	v_cvt_pk_bf16_f32 v8, v8, v9
	v_cvt_pk_bf16_f32 v9, v10, v11
	v_cvt_pk_bf16_f32 v10, v12, v13
	v_cvt_pk_bf16_f32 v11, v14, v15
	ds_write_b128 v172, v[8:11] offset:45824
	v_pk_mul_f32 v[8:9], v[2:3], s[2:3] op_sel_hi:[1,0]
	v_pk_mul_f32 v[10:11], v[0:1], s[2:3] op_sel_hi:[1,0]
	v_pk_mul_f32 v[12:13], v[6:7], s[2:3] op_sel_hi:[1,0]
	v_pk_mul_f32 v[14:15], v[4:5], s[2:3] op_sel_hi:[1,0]
	v_cndmask_b32_e32 v7, v7, v13, vcc
	v_cndmask_b32_e32 v6, v6, v12, vcc
	v_cndmask_b32_e32 v5, v5, v15, vcc
	v_cndmask_b32_e32 v4, v4, v14, vcc
	v_cndmask_b32_e32 v3, v3, v9, vcc
	v_cndmask_b32_e32 v2, v2, v8, vcc
	v_cndmask_b32_e32 v1, v1, v11, vcc
	v_cndmask_b32_e32 v0, v0, v10, vcc
	s_mul_hi_i32 s0, s4, 0x1100
	s_mul_i32 s1, s4, 0x1100
	v_readlane_b32 s4, v245, 55
	v_cvt_pk_bf16_f32 v0, v0, v1
	v_cvt_pk_bf16_f32 v1, v2, v3
	v_cvt_pk_bf16_f32 v2, v4, v5
	v_cvt_pk_bf16_f32 v3, v6, v7
	v_readlane_b32 s5, v245, 56
	s_add_u32 s4, s4, s1
	ds_write_b128 v172, v[0:3] offset:45888
	s_waitcnt lgkmcnt(0)
	s_barrier
	s_addc_u32 s5, s5, s0
	s_lshl_b64 s[0:1], s[6:7], 1
	ds_read_b128 v[0:3], v166 offset:32768
	ds_read_b128 v[4:7], v166 offset:37120
	s_add_u32 s0, s4, s0
	s_addc_u32 s1, s5, s1
	v_lshl_add_u64 v[12:13], s[0:1], 0, v[92:93]
	v_lshl_add_u64 v[8:9], v[94:95], 1, v[12:13]
	s_waitcnt lgkmcnt(1)
	global_store_dwordx4 v[8:9], v[0:3], off nt
	v_lshl_add_u64 v[14:15], v[100:101], 1, v[12:13]
	s_mov_b64 s[10:11], -1
	v_add_co_u32_e32 v0, vcc, s20, v8
	s_nop 1
	v_addc_co_u32_e32 v1, vcc, 0, v9, vcc
	s_waitcnt lgkmcnt(0)
	global_store_dwordx4 v[0:1], v[4:7], off nt
	ds_read_b128 v[0:3], v166 offset:41472
	ds_read_b128 v[4:7], v166 offset:45824
	v_add_co_u32_e32 v8, vcc, s3, v8
	s_nop 1
	v_addc_co_u32_e32 v9, vcc, 0, v9, vcc
	s_waitcnt lgkmcnt(1)
	global_store_dwordx4 v[8:9], v[0:3], off nt
	ds_read_b128 v[0:3], v166 offset:50176
	v_lshl_add_u64 v[8:9], v[96:97], 1, v[12:13]
	s_waitcnt lgkmcnt(1)
	global_store_dwordx4 v[8:9], v[4:7], off nt
	v_lshl_add_u64 v[8:9], v[98:99], 1, v[12:13]
	ds_read_b128 v[4:7], v166 offset:54528
	s_waitcnt lgkmcnt(1)
	global_store_dwordx4 v[8:9], v[0:3], off nt
	ds_read_b128 v[0:3], v166 offset:58880
	ds_read_b128 v[8:11], v166 offset:63232
	s_andn2_b64 vcc, exec, s[8:9]
	s_waitcnt lgkmcnt(2)
	global_store_dwordx4 v[14:15], v[4:7], off nt
	s_nop 1
	v_lshl_add_u64 v[4:5], v[102:103], 1, v[12:13]
	s_waitcnt lgkmcnt(1)
	global_store_dwordx4 v[4:5], v[0:3], off nt
	s_nop 1
	v_lshl_add_u64 v[0:1], v[104:105], 1, v[12:13]
	s_waitcnt lgkmcnt(0)
	global_store_dwordx4 v[0:1], v[8:11], off nt
	s_cbranch_vccz .LBB0_188
	.p2alignl 6, 3212836864

; __device__ __forceinline__ u32x4 pack8(f32x4 a, f32x4 b) { u32x4 r; r.x = cvt_pk_bf16(a[0], a[1]); r.y = cvt_pk_bf16(a[2], a[3]); r.z = cvt_pk_bf16(b[0], b[1]); r.w = cvt_pk_bf16(b[2], b[3]); return r; }
; template <class Epi>
; __device__ __forceinline__ void gemm_tile(const bf16_t* __restrict__ A, const bf16_t* __restrict__ Bt, int K, int row0, int col0, const Epi& epi, char* smem,
;                                           bool prefetched, bool nvalid, int nrow0, int ncol0) {
;     ...
;     if constexpr (Epi::STAGED) {
;         bf16_t* st = (bf16_t*)(smem + 2 * TILE_B);
;         epi.to_lds(acc, st, row0, col0, wr, wc, fr, fq);
;         __syncthreads();
;         bf16_t* gbase; size_t gstride;
;         epi.dest(row0, col0, gbase, gstride);
;         const int r0 = tid >> 4, ch = (tid & 15) * 8;
; #pragma unroll
;         for (int it = 0; it < 8; ++it) { const int r = it * 16 + r0; __builtin_nontemporal_store(*(const u32x4*)(st + r * 136 + ch), (u32x4*)(gbase + (size_t)r * gstride + ch)); }
;     __device__ __forceinline__ void to_lds(f32x4 (&acc)[4][4], bf16_t* st, int row0, int col0, int wr, int wc, int fr, int fq) const {
; #pragma unroll
;         for (int m = 0; m < 4; ++m)
; #pragma unroll
;             for (int pp = 0; pp < 2; ++pp)
;                 *(u32x4*)(st + (wr * 64 + m * 16 + fr) * 136 + wc * 64 + pp * 32 + 8 * fq) = pack8(acc[m][2 * pp], acc[m][2 * pp + 1]);
.LBB0_191:
	s_ashr_i32 s6, s0, 12
	s_ashr_i32 s7, s6, 31
	s_lshl_b64 s[6:7], s[6:7], 22
	s_lshl_b64 s[2:3], s[2:3], 13
	v_readlane_b32 s1, v245, 57
	s_add_u32 s1, s1, s6
	v_readlane_b32 s6, v245, 58
	s_addc_u32 s6, s6, s7
	s_add_u32 s1, s1, s2
	v_cvt_pk_bf16_f32 v56, v56, v57
	v_cvt_pk_bf16_f32 v57, v58, v59
	v_cvt_pk_bf16_f32 v58, v60, v61
	v_cvt_pk_bf16_f32 v59, v62, v63
	v_cvt_pk_bf16_f32 v48, v48, v49
	v_cvt_pk_bf16_f32 v49, v50, v51
	v_cvt_pk_bf16_f32 v50, v52, v53
	v_cvt_pk_bf16_f32 v51, v54, v55
	v_cvt_pk_bf16_f32 v44, v44, v45
	v_cvt_pk_bf16_f32 v45, v46, v47
	v_cvt_pk_bf16_f32 v46, v40, v41
	v_cvt_pk_bf16_f32 v47, v42, v43
	v_cvt_pk_bf16_f32 v36, v36, v37
	v_cvt_pk_bf16_f32 v37, v38, v39
	v_cvt_pk_bf16_f32 v38, v32, v33
	v_cvt_pk_bf16_f32 v39, v34, v35
	v_cvt_pk_bf16_f32 v28, v28, v29
	v_cvt_pk_bf16_f32 v29, v30, v31
	v_cvt_pk_bf16_f32 v30, v24, v25
	v_cvt_pk_bf16_f32 v31, v26, v27
	v_cvt_pk_bf16_f32 v20, v20, v21
	v_cvt_pk_bf16_f32 v21, v22, v23
	v_cvt_pk_bf16_f32 v22, v16, v17
	v_cvt_pk_bf16_f32 v23, v18, v19
	v_cvt_pk_bf16_f32 v4, v4, v5
	v_cvt_pk_bf16_f32 v5, v6, v7
	v_cvt_pk_bf16_f32 v6, v8, v9
	v_cvt_pk_bf16_f32 v7, v10, v11
	v_cvt_pk_bf16_f32 v0, v0, v1
	v_cvt_pk_bf16_f32 v1, v2, v3
	v_cvt_pk_bf16_f32 v2, v12, v13
	v_cvt_pk_bf16_f32 v3, v14, v15
	s_addc_u32 s2, s6, s3
	s_and_b32 s0, s0, 0xf80
	ds_write_b128 v145, v[56:59] offset:32768
	ds_write_b128 v145, v[48:51] offset:32832
	ds_write_b128 v145, v[44:47] offset:37120
	ds_write_b128 v145, v[36:39] offset:37184
	ds_write_b128 v145, v[28:31] offset:41472
	ds_write_b128 v145, v[20:23] offset:41536
	ds_write_b128 v145, v[4:7] offset:45824
	ds_write_b128 v145, v[0:3] offset:45888
	s_waitcnt lgkmcnt(0)
	s_barrier
	s_lshl_b32 s0, s0, 1
	ds_read_b128 v[0:3], v162 offset:32768
	ds_read_b128 v[4:7], v162 offset:37120
	s_add_u32 s0, s1, s0
	s_addc_u32 s1, s2, 0
	v_lshl_add_u64 v[12:13], s[0:1], 0, v[72:73]
	v_lshl_add_u64 v[8:9], v[74:75], 1, v[12:13]
	s_waitcnt lgkmcnt(1)
	global_store_dwordx4 v[8:9], v[0:3], off nt
	ds_read_b128 v[0:3], v162 offset:41472
	v_lshl_add_u64 v[8:9], v[76:77], 1, v[12:13]
	s_waitcnt lgkmcnt(1)
	global_store_dwordx4 v[8:9], v[4:7], off nt
	ds_read_b128 v[4:7], v162 offset:45824
	v_lshl_add_u64 v[8:9], v[78:79], 1, v[12:13]
	s_waitcnt lgkmcnt(1)
	global_store_dwordx4 v[8:9], v[0:3], off nt
	ds_read_b128 v[0:3], v162 offset:50176
	v_lshl_add_u64 v[8:9], v[80:81], 1, v[12:13]
	s_waitcnt lgkmcnt(1)
	global_store_dwordx4 v[8:9], v[4:7], off nt
	v_lshl_add_u64 v[8:9], v[82:83], 1, v[12:13]
	ds_read_b128 v[4:7], v162 offset:54528
	s_waitcnt lgkmcnt(1)
	global_store_dwordx4 v[8:9], v[0:3], off nt
	ds_read_b128 v[0:3], v162 offset:58880
	ds_read_b128 v[8:11], v162 offset:63232
	v_lshl_add_u64 v[14:15], v[84:85], 1, v[12:13]
	s_waitcnt lgkmcnt(2)
	global_store_dwordx4 v[14:15], v[4:7], off nt
	s_andn2_b64 vcc, exec, s[4:5]
	s_mov_b64 s[8:9], -1
	v_lshl_add_u64 v[4:5], v[86:87], 1, v[12:13]
	s_waitcnt lgkmcnt(1)
	global_store_dwordx4 v[4:5], v[0:3], off nt
	s_nop 1
	v_lshl_add_u64 v[0:1], v[88:89], 1, v[12:13]
	s_waitcnt lgkmcnt(0)
	global_store_dwordx4 v[0:1], v[8:11], off nt
	s_cbranch_vccz .LBB0_200
	.p2alignl 6, 3212836864

; __device__ __forceinline__ u32x2 pack4(f32x4 v) { u32x2 r; r.x = cvt_pk_bf16(v[0], v[1]); r.y = cvt_pk_bf16(v[2], v[3]); return r; }
; __device__ __forceinline__ f32x4 zero4() { return (f32x4){0.f, 0.f, 0.f, 0.f}; }
; __device__ __forceinline__ void compress_task(const Params& p, int task, char* smem) {
;     ...
;         if (n >= 255) o = zero4();
;         *(u32x2*)(kc + ((size_t)bg * 256 + n) * 64 + w * 16 + fq * 4) = pack4(o);
;     } else {
;         bf16_t* vct = (bf16_t*)(p.ws + OFF_VCT);
; #pragma unroll
;         for (int j = 0; j < 4; ++j) if (n0 + fq * 4 + j >= 255) o[j] = 0.f;
;         *(u32x2*)(vct + (((size_t)bg * 16 + (n0 >> 4)) * 64 + w * 16 + fr) * 16 + fq * 4) = pack4(o);
;     }
;     __syncthreads();
; __global__ void __launch_bounds__(256, 2) fwd_megakernel(Params p) {
;     ...
;     for (int task = blockIdx.x; task < 1024; task += G) compress_task(p, task, smem);
.LBB0_248:
	v_lshl_add_u64 v[0:1], v[64:65], 1, v[6:7]
	v_mov_b32_e32 v89, v65
	s_add_i32 s42, s42, s58
	s_add_i32 s20, s20, s21
	v_lshl_add_u64 v[0:1], v[0:1], 0, v[88:89]
	s_cmpk_gt_i32 s42, 0x3ff
	global_store_dwordx2 v[0:1], v[4:5], off
	s_waitcnt lgkmcnt(0)
	s_barrier
	s_cbranch_scc1 .LBB0_292
	.p2alignl 6, 3212836864

; __global__ void __launch_bounds__(256, 2) fwd_megakernel(Params p) {
;     ...
;     for (int r = 0; r * G < 4096; ++r) {
;         const int k = (r & 1) ? (G - 1 - (int)blockIdx.x) : (int)blockIdx.x, i = r * G + k;
;         if (i < 4096) nsa_tile(p, 127 - (i >> 5), i & 31, smem);
.LBB0_339:
	s_add_i32 s3, s3, 1
	s_mul_i32 s0, s3, s58
	s_cmpk_gt_i32 s0, 0xfff
	s_cbranch_scc1 .LBB0_408
	.p2alignl 6, 3212836864

;     __device__ __forceinline__ void operator()(f32x4 (&acc)[4][4], int rb, int cb, int fr, int fq) const {
;         f32x4 r[4][2][2];
; #pragma unroll
;         for (int m = 0; m < 4; ++m)
; #pragma unroll
;             for (int pp = 0; pp < 2; ++pp) {
;                 const size_t o = (size_t)(rb + m * 16 + fr) * D + cb + pp * 32 + 8 * fq;
;                 r[m][pp][0] = __builtin_nontemporal_load((const f32x4*)(res + o));
;                 r[m][pp][1] = __builtin_nontemporal_load((const f32x4*)(res + o + 4));
;             }
; #pragma unroll
;         for (int m = 0; m < 4; ++m)
; #pragma unroll
;             for (int pp = 0; pp < 2; ++pp) {
;                 const size_t o = (size_t)(rb + m * 16 + fr) * D + cb + pp * 32 + 8 * fq;
;                 *(f32x4*)(out + o) = r[m][pp][0] + acc[m][2 * pp];
;                 *(f32x4*)(out + o + 4) = r[m][pp][1] + acc[m][2 * pp + 1];
;             }
;     }
.LBB0_454:
	v_add_u32_e32 v182, s0, v85
	v_or_b32_e32 v130, s4, v148
	v_or_b32_e32 v142, 16, v182
	v_or_b32_e32 v174, 32, v182
	v_or_b32_e32 v192, 48, v182
	v_ashrrev_i32_e32 v131, 31, v130
	v_ashrrev_i32_e32 v183, 31, v182
	v_ashrrev_i32_e32 v143, 31, v142
	v_ashrrev_i32_e32 v175, 31, v174
	v_ashrrev_i32_e32 v193, 31, v192
	v_lshl_add_u64 v[190:191], v[130:131], 2, v[72:73]
	v_lshlrev_b64 v[206:207], 12, v[182:183]
	v_lshlrev_b64 v[208:209], 12, v[142:143]
	v_lshlrev_b64 v[210:211], 12, v[174:175]
	v_lshlrev_b64 v[212:213], 12, v[192:193]
	v_lshl_add_u64 v[106:107], v[190:191], 0, v[206:207]
	v_lshl_add_u64 v[170:171], v[190:191], 0, v[208:209]
	v_lshl_add_u64 v[186:187], v[190:191], 0, v[210:211]
	v_lshl_add_u64 v[202:203], v[190:191], 0, v[212:213]
	global_load_dwordx4 v[94:97], v[106:107], off nt
	global_load_dwordx4 v[98:101], v[106:107], off offset:16 nt
	global_load_dwordx4 v[102:105], v[106:107], off offset:128 nt
	s_nop 0
	global_load_dwordx4 v[106:109], v[106:107], off offset:144 nt
	s_nop 0
	global_load_dwordx4 v[142:145], v[170:171], off nt
	global_load_dwordx4 v[162:165], v[170:171], off offset:16 nt
	global_load_dwordx4 v[166:169], v[170:171], off offset:144 nt
	s_nop 0
	global_load_dwordx4 v[170:173], v[170:171], off offset:128 nt
	s_nop 0
	global_load_dwordx4 v[174:177], v[186:187], off nt
	global_load_dwordx4 v[178:181], v[186:187], off offset:16 nt
	global_load_dwordx4 v[182:185], v[186:187], off offset:144 nt
	s_nop 0
	global_load_dwordx4 v[186:189], v[186:187], off offset:128 nt
	s_nop 0
	global_load_dwordx4 v[190:193], v[202:203], off nt
	global_load_dwordx4 v[194:197], v[202:203], off offset:16 nt
	global_load_dwordx4 v[198:201], v[202:203], off offset:128 nt
	s_nop 0
	global_load_dwordx4 v[202:205], v[202:203], off offset:144 nt
	v_or_b32_e32 v130, v130, v84
	v_lshlrev_b64 v[130:131], 2, v[130:131]
	v_lshl_add_u64 v[214:215], s[54:55], 0, v[130:131]
	v_lshl_add_u64 v[208:209], s[54:55], 0, v[208:209]
	v_lshl_add_u64 v[210:211], s[54:55], 0, v[210:211]
	v_lshl_add_u64 v[212:213], s[54:55], 0, v[212:213]
	v_lshl_add_u64 v[206:207], v[214:215], 0, v[206:207]
	v_lshl_add_u64 v[208:209], v[208:209], 0, v[130:131]
	v_lshl_add_u64 v[210:211], v[210:211], 0, v[130:131]
	v_lshl_add_u64 v[130:131], v[212:213], 0, v[130:131]
	s_andn2_b64 vcc, exec, s[6:7]
	s_mov_b64 s[10:11], -1
	s_waitcnt vmcnt(0)
	v_pk_add_f32 v[54:55], v[54:55], v[96:97]
	v_pk_add_f32 v[52:53], v[52:53], v[94:95]
	v_pk_add_f32 v[58:59], v[58:59], v[100:101]
	v_pk_add_f32 v[46:47], v[46:47], v[144:145]
	v_pk_add_f32 v[44:45], v[44:45], v[142:143]
	v_pk_add_f32 v[56:57], v[56:57], v[98:99]
	v_pk_add_f32 v[62:63], v[62:63], v[104:105]
	v_pk_add_f32 v[6:7], v[6:7], v[200:201]
	v_pk_add_f32 v[4:5], v[4:5], v[198:199]
	v_pk_add_f32 v[2:3], v[2:3], v[204:205]
	v_pk_add_f32 v[0:1], v[0:1], v[202:203]
	v_pk_add_f32 v[60:61], v[60:61], v[102:103]
	v_pk_add_f32 v[50:51], v[50:51], v[108:109]
	v_pk_add_f32 v[48:49], v[48:49], v[106:107]
	global_store_dwordx4 v[206:207], v[52:55], off
	global_store_dwordx4 v[206:207], v[56:59], off offset:16
	global_store_dwordx4 v[206:207], v[60:63], off offset:128
	global_store_dwordx4 v[206:207], v[48:51], off offset:144
	v_pk_add_f32 v[42:43], v[42:43], v[164:165]
	v_pk_add_f32 v[40:41], v[40:41], v[162:163]
	v_pk_add_f32 v[34:35], v[34:35], v[172:173]
	v_pk_add_f32 v[32:33], v[32:33], v[170:171]
	v_pk_add_f32 v[26:27], v[26:27], v[168:169]
	v_pk_add_f32 v[24:25], v[24:25], v[166:167]
	v_pk_add_f32 v[38:39], v[38:39], v[176:177]
	v_pk_add_f32 v[36:37], v[36:37], v[174:175]
	v_pk_add_f32 v[30:31], v[30:31], v[180:181]
	v_pk_add_f32 v[28:29], v[28:29], v[178:179]
	v_pk_add_f32 v[22:23], v[22:23], v[188:189]
	v_pk_add_f32 v[20:21], v[20:21], v[186:187]
	v_pk_add_f32 v[18:19], v[18:19], v[184:185]
	v_pk_add_f32 v[16:17], v[16:17], v[182:183]
	v_pk_add_f32 v[14:15], v[14:15], v[192:193]
	v_pk_add_f32 v[12:13], v[12:13], v[190:191]
	v_pk_add_f32 v[10:11], v[10:11], v[196:197]
	v_pk_add_f32 v[8:9], v[8:9], v[194:195]
	global_store_dwordx4 v[208:209], v[44:47], off
	global_store_dwordx4 v[208:209], v[40:43], off offset:16
	global_store_dwordx4 v[208:209], v[32:35], off offset:128
	global_store_dwordx4 v[208:209], v[24:27], off offset:144
	global_store_dwordx4 v[210:211], v[36:39], off
	global_store_dwordx4 v[210:211], v[28:31], off offset:16
	global_store_dwordx4 v[210:211], v[20:23], off offset:128
	global_store_dwordx4 v[210:211], v[16:19], off offset:144
	global_store_dwordx4 v[130:131], v[12:15], off
	global_store_dwordx4 v[130:131], v[8:11], off offset:16
	global_store_dwordx4 v[130:131], v[4:7], off offset:128
	global_store_dwordx4 v[130:131], v[0:3], off offset:144
	s_cbranch_vccz .LBB0_463
	.p2alignl 6, 3212836864

; __device__ __forceinline__ u32x4 pack8(f32x4 a, f32x4 b) { u32x4 r; r.x = cvt_pk_bf16(a[0], a[1]); r.y = cvt_pk_bf16(a[2], a[3]); r.z = cvt_pk_bf16(b[0], b[1]); r.w = cvt_pk_bf16(b[2], b[3]); return r; }
;     __device__ __forceinline__ void to_lds(f32x4 (&acc)[4][4], bf16_t* st, int row0, int col0, int wr, int wc, int fr, int fq) const {
; #pragma unroll
;         for (int m = 0; m < 4; ++m)
; #pragma unroll
;             for (int pp = 0; pp < 2; ++pp) {
;                 f32x4 v0 = acc[m][2 * pp], v1 = acc[m][2 * pp + 1];
; #pragma unroll
;                 for (int j = 0; j < 4; ++j) { const float u0 = fmaxf(v0[j], 0.f), u1 = fmaxf(v1[j], 0.f); v0[j] = u0 * u0; v1[j] = u1 * u1; }
;                 *(u32x4*)(st + (wr * 64 + m * 16 + fr) * 136 + wc * 64 + pp * 32 + 8 * fq) = pack8(v0, v1);
;             }
;     }
.LBB0_557:
	v_max_f32_e32 v48, v48, v48
	v_max_f32_e32 v52, v52, v52
	v_max_f32_e32 v49, v49, v49
	v_max_f32_e32 v53, v53, v53
	v_max_f32_e32 v50, v50, v50
	v_max_f32_e32 v54, v54, v54
	v_max_f32_e32 v51, v51, v51
	v_max_f32_e32 v55, v55, v55
	v_max_f32_e32 v48, 0, v48
	v_max_f32_e32 v52, 0, v52
	v_max_f32_e32 v49, 0, v49
	v_max_f32_e32 v53, 0, v53
	v_max_f32_e32 v50, 0, v50
	v_max_f32_e32 v54, 0, v54
	v_max_f32_e32 v51, 0, v51
	v_max_f32_e32 v55, 0, v55
	v_pk_mul_f32 v[48:49], v[48:49], v[48:49]
	v_pk_mul_f32 v[52:53], v[52:53], v[52:53]
	v_pk_mul_f32 v[50:51], v[50:51], v[50:51]
	v_pk_mul_f32 v[54:55], v[54:55], v[54:55]
	v_max_f32_e32 v40, v40, v40
	v_max_f32_e32 v41, v41, v41
	v_cvt_pk_bf16_f32 v48, v48, v49
	v_cvt_pk_bf16_f32 v49, v50, v51
	v_cvt_pk_bf16_f32 v50, v52, v53
	v_cvt_pk_bf16_f32 v51, v54, v55
	v_max_f32_e32 v40, 0, v40
	v_max_f32_e32 v41, 0, v41
	ds_write_b128 v166, v[48:51] offset:32832
	v_pk_mul_f32 v[48:49], v[40:41], v[40:41]
	v_max_f32_e32 v41, v42, v42
	v_max_f32_e32 v44, v44, v44
	v_max_f32_e32 v45, v45, v45
	v_max_f32_e32 v40, v46, v46
	v_max_f32_e32 v42, 0, v41
	v_max_f32_e32 v41, v47, v47
	v_max_f32_e32 v43, v43, v43
	v_max_f32_e32 v44, 0, v44
	v_max_f32_e32 v45, 0, v45
	v_max_f32_e32 v40, 0, v40
	v_max_f32_e32 v41, 0, v41
	v_max_f32_e32 v43, 0, v43
	v_pk_mul_f32 v[44:45], v[44:45], v[44:45]
	v_pk_mul_f32 v[46:47], v[40:41], v[40:41]
	v_pk_mul_f32 v[50:51], v[42:43], v[42:43]
	v_max_f32_e32 v32, v32, v32
	v_max_f32_e32 v33, v33, v33
	v_cvt_pk_bf16_f32 v40, v44, v45
	v_cvt_pk_bf16_f32 v41, v46, v47
	v_cvt_pk_bf16_f32 v42, v48, v49
	v_cvt_pk_bf16_f32 v43, v50, v51
	v_max_f32_e32 v32, 0, v32
	v_max_f32_e32 v33, 0, v33
	ds_write_b128 v166, v[40:43] offset:37120
	v_pk_mul_f32 v[40:41], v[32:33], v[32:33]
	v_max_f32_e32 v33, v34, v34
	v_max_f32_e32 v36, v36, v36
	v_max_f32_e32 v37, v37, v37
	v_max_f32_e32 v32, v38, v38
	v_max_f32_e32 v34, 0, v33
	v_max_f32_e32 v33, v39, v39
	v_max_f32_e32 v35, v35, v35
	v_max_f32_e32 v36, 0, v36
	v_max_f32_e32 v37, 0, v37
	v_max_f32_e32 v32, 0, v32
	v_max_f32_e32 v33, 0, v33
	v_max_f32_e32 v35, 0, v35
	v_pk_mul_f32 v[36:37], v[36:37], v[36:37]
	v_pk_mul_f32 v[38:39], v[32:33], v[32:33]
	v_pk_mul_f32 v[42:43], v[34:35], v[34:35]
	v_max_f32_e32 v24, v24, v24
	v_max_f32_e32 v25, v25, v25
	v_cvt_pk_bf16_f32 v32, v36, v37
	v_cvt_pk_bf16_f32 v33, v38, v39
	v_cvt_pk_bf16_f32 v34, v40, v41
	v_cvt_pk_bf16_f32 v35, v42, v43
	v_max_f32_e32 v24, 0, v24
	v_max_f32_e32 v25, 0, v25
	ds_write_b128 v166, v[32:35] offset:37184
	v_pk_mul_f32 v[32:33], v[24:25], v[24:25]
	v_max_f32_e32 v25, v26, v26
	v_max_f32_e32 v28, v28, v28
	v_max_f32_e32 v29, v29, v29
	v_max_f32_e32 v24, v30, v30
	v_max_f32_e32 v26, 0, v25
	v_max_f32_e32 v25, v31, v31
	v_max_f32_e32 v27, v27, v27
	v_max_f32_e32 v28, 0, v28
	v_max_f32_e32 v29, 0, v29
	v_max_f32_e32 v24, 0, v24
	v_max_f32_e32 v25, 0, v25
	v_max_f32_e32 v27, 0, v27
	v_pk_mul_f32 v[28:29], v[28:29], v[28:29]
	v_pk_mul_f32 v[30:31], v[24:25], v[24:25]
	v_pk_mul_f32 v[34:35], v[26:27], v[26:27]
	v_max_f32_e32 v16, v16, v16
	v_max_f32_e32 v17, v17, v17
	v_cvt_pk_bf16_f32 v24, v28, v29
	v_cvt_pk_bf16_f32 v25, v30, v31
	v_cvt_pk_bf16_f32 v26, v32, v33
	v_cvt_pk_bf16_f32 v27, v34, v35
	v_max_f32_e32 v16, 0, v16
	v_max_f32_e32 v17, 0, v17
	ds_write_b128 v166, v[24:27] offset:41472
	v_pk_mul_f32 v[24:25], v[16:17], v[16:17]
	v_max_f32_e32 v17, v18, v18
	v_max_f32_e32 v56, v56, v56
	v_max_f32_e32 v60, v60, v60
	v_max_f32_e32 v57, v57, v57
	v_max_f32_e32 v61, v61, v61
	v_max_f32_e32 v58, v58, v58
	v_max_f32_e32 v62, v62, v62
	v_max_f32_e32 v59, v59, v59
	v_max_f32_e32 v63, v63, v63
	v_max_f32_e32 v20, v20, v20
	v_max_f32_e32 v21, v21, v21
	v_max_f32_e32 v16, v22, v22
	v_max_f32_e32 v18, 0, v17
	v_max_f32_e32 v17, v23, v23
	v_max_f32_e32 v19, v19, v19
	v_max_f32_e32 v8, v8, v8
	v_max_f32_e32 v12, v12, v12
	v_max_f32_e32 v9, v9, v9
	v_max_f32_e32 v13, v13, v13
	v_max_f32_e32 v10, v10, v10
	v_max_f32_e32 v14, v14, v14
	v_max_f32_e32 v11, v11, v11
	v_max_f32_e32 v15, v15, v15
	v_max_f32_e32 v0, v0, v0
	v_max_f32_e32 v4, v4, v4
	v_max_f32_e32 v1, v1, v1
	v_max_f32_e32 v5, v5, v5
	v_max_f32_e32 v2, v2, v2
	v_max_f32_e32 v6, v6, v6
	v_max_f32_e32 v3, v3, v3
	v_max_f32_e32 v7, v7, v7
	v_max_f32_e32 v56, 0, v56
	v_max_f32_e32 v60, 0, v60
	v_max_f32_e32 v57, 0, v57
	v_max_f32_e32 v61, 0, v61
	v_max_f32_e32 v58, 0, v58
	v_max_f32_e32 v62, 0, v62
	v_max_f32_e32 v59, 0, v59
	v_max_f32_e32 v63, 0, v63
	v_max_f32_e32 v20, 0, v20
	v_max_f32_e32 v21, 0, v21
	v_max_f32_e32 v16, 0, v16
	v_max_f32_e32 v17, 0, v17
	v_max_f32_e32 v19, 0, v19
	v_max_f32_e32 v8, 0, v8
	v_max_f32_e32 v12, 0, v12
	v_max_f32_e32 v9, 0, v9
	v_max_f32_e32 v13, 0, v13
	v_max_f32_e32 v10, 0, v10
	v_max_f32_e32 v14, 0, v14
	v_max_f32_e32 v11, 0, v11
	v_max_f32_e32 v15, 0, v15
	v_max_f32_e32 v0, 0, v0
	v_max_f32_e32 v4, 0, v4
	v_max_f32_e32 v1, 0, v1
	v_max_f32_e32 v5, 0, v5
	v_max_f32_e32 v2, 0, v2
	v_max_f32_e32 v6, 0, v6
	v_max_f32_e32 v3, 0, v3
	v_max_f32_e32 v7, 0, v7
	v_pk_mul_f32 v[56:57], v[56:57], v[56:57]
	v_pk_mul_f32 v[60:61], v[60:61], v[60:61]
	v_pk_mul_f32 v[58:59], v[58:59], v[58:59]
	v_pk_mul_f32 v[62:63], v[62:63], v[62:63]
	v_pk_mul_f32 v[20:21], v[20:21], v[20:21]
	v_pk_mul_f32 v[22:23], v[16:17], v[16:17]
	v_pk_mul_f32 v[26:27], v[18:19], v[18:19]
	v_pk_mul_f32 v[8:9], v[8:9], v[8:9]
	v_pk_mul_f32 v[12:13], v[12:13], v[12:13]
	v_pk_mul_f32 v[10:11], v[10:11], v[10:11]
	v_pk_mul_f32 v[14:15], v[14:15], v[14:15]
	v_pk_mul_f32 v[0:1], v[0:1], v[0:1]
	v_pk_mul_f32 v[4:5], v[4:5], v[4:5]
	v_pk_mul_f32 v[2:3], v[2:3], v[2:3]
	v_pk_mul_f32 v[6:7], v[6:7], v[6:7]
	s_lshl_b64 s[0:1], s[0:1], 13
	v_readlane_b32 s8, v245, 55
	v_cvt_pk_bf16_f32 v56, v56, v57
	v_cvt_pk_bf16_f32 v57, v58, v59
	v_cvt_pk_bf16_f32 v58, v60, v61
	v_cvt_pk_bf16_f32 v59, v62, v63
	v_cvt_pk_bf16_f32 v16, v20, v21
	v_cvt_pk_bf16_f32 v17, v22, v23
	v_cvt_pk_bf16_f32 v18, v24, v25
	v_cvt_pk_bf16_f32 v19, v26, v27
	v_cvt_pk_bf16_f32 v8, v8, v9
	v_cvt_pk_bf16_f32 v9, v10, v11
	v_cvt_pk_bf16_f32 v10, v12, v13
	v_cvt_pk_bf16_f32 v11, v14, v15
	v_cvt_pk_bf16_f32 v0, v0, v1
	v_cvt_pk_bf16_f32 v1, v2, v3
	v_cvt_pk_bf16_f32 v2, v4, v5
	v_cvt_pk_bf16_f32 v3, v6, v7
	v_readlane_b32 s9, v245, 56
	s_add_u32 s8, s8, s0
	ds_write_b128 v166, v[56:59] offset:32768
	ds_write_b128 v166, v[16:19] offset:41536
	ds_write_b128 v166, v[8:11] offset:45824
	ds_write_b128 v166, v[0:3] offset:45888
	s_waitcnt lgkmcnt(0)
	s_barrier
; template <class Epi>
; __device__ __forceinline__ void gemm_tile(const bf16_t* __restrict__ A, const bf16_t* __restrict__ Bt, int K, int row0, int col0, const Epi& epi, char* smem,
;                                           bool prefetched, bool nvalid, int nrow0, int ncol0) {
;     ...
;         __syncthreads();
;         bf16_t* gbase; size_t gstride;
;         epi.dest(row0, col0, gbase, gstride);
;         const int r0 = tid >> 4, ch = (tid & 15) * 8;
; #pragma unroll
;         for (int it = 0; it < 8; ++it) { const int r = it * 16 + r0; __builtin_nontemporal_store(*(const u32x4*)(st + r * 136 + ch), (u32x4*)(gbase + (size_t)r * gstride + ch)); }
	s_addc_u32 s9, s9, s1
	s_lshl_b64 s[0:1], s[4:5], 1
	ds_read_b128 v[0:3], v167 offset:32768
	ds_read_b128 v[4:7], v167 offset:37120
	s_add_u32 s0, s8, s0
	s_addc_u32 s1, s9, s1
	v_lshl_add_u64 v[12:13], s[0:1], 0, v[72:73]
	v_lshl_add_u64 v[8:9], v[74:75], 1, v[12:13]
	s_waitcnt lgkmcnt(1)
	global_store_dwordx4 v[8:9], v[0:3], off nt
	ds_read_b128 v[0:3], v167 offset:41472
	v_lshl_add_u64 v[8:9], v[76:77], 1, v[12:13]
	s_waitcnt lgkmcnt(1)
	global_store_dwordx4 v[8:9], v[4:7], off nt
	ds_read_b128 v[4:7], v167 offset:45824
	v_lshl_add_u64 v[8:9], v[78:79], 1, v[12:13]
	s_waitcnt lgkmcnt(1)
	global_store_dwordx4 v[8:9], v[0:3], off nt
	ds_read_b128 v[0:3], v167 offset:50176
	v_lshl_add_u64 v[8:9], v[80:81], 1, v[12:13]
	s_waitcnt lgkmcnt(1)
	global_store_dwordx4 v[8:9], v[4:7], off nt
	v_lshl_add_u64 v[8:9], v[82:83], 1, v[12:13]
	ds_read_b128 v[4:7], v167 offset:54528
	s_waitcnt lgkmcnt(1)
	global_store_dwordx4 v[8:9], v[0:3], off nt
	ds_read_b128 v[0:3], v167 offset:58880
	ds_read_b128 v[8:11], v167 offset:63232
	v_lshl_add_u64 v[14:15], v[88:89], 1, v[12:13]
	s_waitcnt lgkmcnt(2)
	global_store_dwordx4 v[14:15], v[4:7], off nt
	s_andn2_b64 vcc, exec, s[6:7]
	s_mov_b64 s[10:11], -1
	v_lshl_add_u64 v[4:5], v[90:91], 1, v[12:13]
	s_waitcnt lgkmcnt(1)
	global_store_dwordx4 v[4:5], v[0:3], off nt
	s_nop 1
	v_lshl_add_u64 v[0:1], v[92:93], 1, v[12:13]
	s_waitcnt lgkmcnt(0)
	global_store_dwordx4 v[0:1], v[8:11], off nt
	s_cbranch_vccz .LBB0_566
	.p2alignl 6, 3212836864

;     __device__ __forceinline__ void operator()(f32x4 (&acc)[4][4], int rb, int cb, int fr, int fq) const {
;         f32x4 r[4][2][2];
; #pragma unroll
;         for (int m = 0; m < 4; ++m)
; #pragma unroll
;             for (int pp = 0; pp < 2; ++pp) {
;                 const size_t o = (size_t)(rb + m * 16 + fr) * D + cb + pp * 32 + 8 * fq;
;                 r[m][pp][0] = __builtin_nontemporal_load((const f32x4*)(res + o));
;                 r[m][pp][1] = __builtin_nontemporal_load((const f32x4*)(res + o + 4));
;             }
; #pragma unroll
;         for (int m = 0; m < 4; ++m)
; #pragma unroll
;             for (int pp = 0; pp < 2; ++pp) {
;                 const size_t o = (size_t)(rb + m * 16 + fr) * D + cb + pp * 32 + 8 * fq;
;                 *(f32x4*)(out + o) = r[m][pp][0] + acc[m][2 * pp];
;                 *(f32x4*)(out + o + 4) = r[m][pp][1] + acc[m][2 * pp + 1];
;             }
;     }
.LBB0_613:
	v_add_u32_e32 v182, s0, v85
	v_or_b32_e32 v130, s2, v148
	v_or_b32_e32 v142, 16, v182
	v_or_b32_e32 v174, 32, v182
	v_or_b32_e32 v192, 48, v182
	v_ashrrev_i32_e32 v131, 31, v130
	v_ashrrev_i32_e32 v183, 31, v182
	v_ashrrev_i32_e32 v143, 31, v142
	v_ashrrev_i32_e32 v175, 31, v174
	v_ashrrev_i32_e32 v193, 31, v192
	v_lshl_add_u64 v[190:191], v[130:131], 2, v[72:73]
	v_lshlrev_b64 v[92:93], 12, v[182:183]
	v_lshlrev_b64 v[208:209], 12, v[142:143]
	v_lshlrev_b64 v[210:211], 12, v[174:175]
	v_lshlrev_b64 v[212:213], 12, v[192:193]
	v_lshl_add_u64 v[206:207], v[190:191], 0, v[92:93]
	v_lshl_add_u64 v[170:171], v[190:191], 0, v[208:209]
	v_lshl_add_u64 v[186:187], v[190:191], 0, v[210:211]
	v_lshl_add_u64 v[202:203], v[190:191], 0, v[212:213]
	global_load_dwordx4 v[92:95], v[206:207], off nt
	global_load_dwordx4 v[96:99], v[206:207], off offset:16 nt
	global_load_dwordx4 v[100:103], v[206:207], off offset:128 nt
	global_load_dwordx4 v[104:107], v[206:207], off offset:144 nt
	global_load_dwordx4 v[142:145], v[170:171], off nt
	global_load_dwordx4 v[162:165], v[170:171], off offset:16 nt
	global_load_dwordx4 v[166:169], v[170:171], off offset:144 nt
	s_nop 0
	global_load_dwordx4 v[170:173], v[170:171], off offset:128 nt
	s_nop 0
	global_load_dwordx4 v[174:177], v[186:187], off nt
	global_load_dwordx4 v[178:181], v[186:187], off offset:16 nt
	global_load_dwordx4 v[182:185], v[186:187], off offset:144 nt
	s_nop 0
	global_load_dwordx4 v[186:189], v[186:187], off offset:128 nt
	s_nop 0
	global_load_dwordx4 v[190:193], v[202:203], off nt
	global_load_dwordx4 v[194:197], v[202:203], off offset:16 nt
	global_load_dwordx4 v[198:201], v[202:203], off offset:128 nt
	s_nop 0
	global_load_dwordx4 v[202:205], v[202:203], off offset:144 nt
	v_or_b32_e32 v130, v130, v84
	v_lshlrev_b64 v[130:131], 2, v[130:131]
	v_lshl_add_u64 v[208:209], s[54:55], 0, v[208:209]
	v_lshl_add_u64 v[210:211], s[54:55], 0, v[210:211]
	v_lshl_add_u64 v[212:213], s[54:55], 0, v[212:213]
	v_lshl_add_u64 v[208:209], v[208:209], 0, v[130:131]
	v_lshl_add_u64 v[210:211], v[210:211], 0, v[130:131]
	v_lshl_add_u64 v[130:131], v[212:213], 0, v[130:131]
	s_andn2_b64 vcc, exec, s[6:7]
	s_mov_b64 s[10:11], -1
	s_waitcnt vmcnt(0)
	v_pk_add_f32 v[54:55], v[54:55], v[94:95]
	v_pk_add_f32 v[52:53], v[52:53], v[92:93]
	v_pk_add_f32 v[58:59], v[58:59], v[98:99]
	v_pk_add_f32 v[46:47], v[46:47], v[144:145]
	v_pk_add_f32 v[44:45], v[44:45], v[142:143]
	v_pk_add_f32 v[56:57], v[56:57], v[96:97]
	v_pk_add_f32 v[62:63], v[62:63], v[102:103]
	v_pk_add_f32 v[60:61], v[60:61], v[100:101]
	v_pk_add_f32 v[2:3], v[2:3], v[204:205]
	v_pk_add_f32 v[0:1], v[0:1], v[202:203]
	v_pk_add_f32 v[50:51], v[50:51], v[106:107]
	v_pk_add_f32 v[48:49], v[48:49], v[104:105]
	global_store_dwordx4 v[206:207], v[52:55], off
	global_store_dwordx4 v[206:207], v[56:59], off offset:16
	global_store_dwordx4 v[206:207], v[60:63], off offset:128
	global_store_dwordx4 v[206:207], v[48:51], off offset:144
	v_pk_add_f32 v[42:43], v[42:43], v[164:165]
	v_pk_add_f32 v[40:41], v[40:41], v[162:163]
	v_pk_add_f32 v[34:35], v[34:35], v[172:173]
	v_pk_add_f32 v[32:33], v[32:33], v[170:171]
	v_pk_add_f32 v[26:27], v[26:27], v[168:169]
	v_pk_add_f32 v[24:25], v[24:25], v[166:167]
	v_pk_add_f32 v[38:39], v[38:39], v[176:177]
	v_pk_add_f32 v[36:37], v[36:37], v[174:175]
	v_pk_add_f32 v[30:31], v[30:31], v[180:181]
	v_pk_add_f32 v[28:29], v[28:29], v[178:179]
	v_pk_add_f32 v[22:23], v[22:23], v[188:189]
	v_pk_add_f32 v[20:21], v[20:21], v[186:187]
	v_pk_add_f32 v[18:19], v[18:19], v[184:185]
	v_pk_add_f32 v[16:17], v[16:17], v[182:183]
	v_pk_add_f32 v[14:15], v[14:15], v[192:193]
	v_pk_add_f32 v[12:13], v[12:13], v[190:191]
	v_pk_add_f32 v[10:11], v[10:11], v[196:197]
	v_pk_add_f32 v[8:9], v[8:9], v[194:195]
	v_pk_add_f32 v[6:7], v[6:7], v[200:201]
	v_pk_add_f32 v[4:5], v[4:5], v[198:199]
	global_store_dwordx4 v[208:209], v[44:47], off
	global_store_dwordx4 v[208:209], v[40:43], off offset:16
	global_store_dwordx4 v[208:209], v[32:35], off offset:128
	global_store_dwordx4 v[208:209], v[24:27], off offset:144
	global_store_dwordx4 v[210:211], v[36:39], off
	global_store_dwordx4 v[210:211], v[28:31], off offset:16
	global_store_dwordx4 v[210:211], v[20:23], off offset:128
	global_store_dwordx4 v[210:211], v[16:19], off offset:144
	global_store_dwordx4 v[130:131], v[12:15], off
	global_store_dwordx4 v[130:131], v[8:11], off offset:16
	global_store_dwordx4 v[130:131], v[4:7], off offset:128
	global_store_dwordx4 v[130:131], v[0:3], off offset:144
	s_cbranch_vccz .LBB0_622
	.p2alignl 6, 3212836864

; __device__ __forceinline__ u32x4 pack8(f32x4 a, f32x4 b) { u32x4 r; r.x = cvt_pk_bf16(a[0], a[1]); r.y = cvt_pk_bf16(a[2], a[3]); r.z = cvt_pk_bf16(b[0], b[1]); r.w = cvt_pk_bf16(b[2], b[3]); return r; }
; template <class Epi>
; __device__ __forceinline__ void gemm_tile(const bf16_t* __restrict__ A, const bf16_t* __restrict__ Bt, int K, int row0, int col0, const Epi& epi, char* smem,
;                                           bool prefetched, bool nvalid, int nrow0, int ncol0) {
;     ...
;     if constexpr (Epi::STAGED) {
;         bf16_t* st = (bf16_t*)(smem + 2 * TILE_B);
;         epi.to_lds(acc, st, row0, col0, wr, wc, fr, fq);
;         __syncthreads();
;         bf16_t* gbase; size_t gstride;
;         epi.dest(row0, col0, gbase, gstride);
;         const int r0 = tid >> 4, ch = (tid & 15) * 8;
; #pragma unroll
;         for (int it = 0; it < 8; ++it) { const int r = it * 16 + r0; __builtin_nontemporal_store(*(const u32x4*)(st + r * 136 + ch), (u32x4*)(gbase + (size_t)r * gstride + ch)); }
;     __device__ __forceinline__ void to_lds(f32x4 (&acc)[4][4], bf16_t* st, int row0, int col0, int wr, int wc, int fr, int fq) const {
;     ...
;                 if (isq) { v0 = v0 * 0.18033688011112042f; v1 = v1 * 0.18033688011112042f; }
;                 *(u32x4*)(st + rl * 136 + wc * 64 + pp * 32 + 8 * fq) = pack8(v0, v1);
.LBB0_717:
	s_or_b64 exec, exec, s[14:15]
	s_waitcnt lgkmcnt(4)
	v_pk_mul_f32 v[16:17], v[10:11], s[2:3] op_sel_hi:[1,0]
	s_waitcnt vmcnt(1)
	v_pk_mul_f32 v[18:19], v[8:9], s[2:3] op_sel_hi:[1,0]
	v_pk_mul_f32 v[20:21], v[14:15], s[2:3] op_sel_hi:[1,0]
	v_pk_mul_f32 v[22:23], v[12:13], s[2:3] op_sel_hi:[1,0]
	v_cndmask_b32_e32 v15, v15, v21, vcc
	v_cndmask_b32_e32 v14, v14, v20, vcc
	v_cndmask_b32_e32 v13, v13, v23, vcc
	v_cndmask_b32_e32 v12, v12, v22, vcc
	v_cndmask_b32_e32 v11, v11, v17, vcc
	v_cndmask_b32_e32 v10, v10, v16, vcc
	v_cndmask_b32_e32 v9, v9, v19, vcc
	v_cndmask_b32_e32 v8, v8, v18, vcc
	v_cvt_pk_bf16_f32 v8, v8, v9
	v_cvt_pk_bf16_f32 v9, v10, v11
	v_cvt_pk_bf16_f32 v10, v12, v13
	v_cvt_pk_bf16_f32 v11, v14, v15
	ds_write_b128 v178, v[8:11] offset:45824
	v_pk_mul_f32 v[8:9], v[2:3], s[2:3] op_sel_hi:[1,0]
	v_pk_mul_f32 v[10:11], v[0:1], s[2:3] op_sel_hi:[1,0]
	v_pk_mul_f32 v[12:13], v[6:7], s[2:3] op_sel_hi:[1,0]
	v_pk_mul_f32 v[14:15], v[4:5], s[2:3] op_sel_hi:[1,0]
	v_cndmask_b32_e32 v7, v7, v13, vcc
	v_cndmask_b32_e32 v6, v6, v12, vcc
	v_cndmask_b32_e32 v5, v5, v15, vcc
	v_cndmask_b32_e32 v4, v4, v14, vcc
	v_cndmask_b32_e32 v3, v3, v9, vcc
	v_cndmask_b32_e32 v2, v2, v8, vcc
	v_cndmask_b32_e32 v1, v1, v11, vcc
	v_cndmask_b32_e32 v0, v0, v10, vcc
	s_mul_hi_i32 s0, s6, 0x1100
	s_mul_i32 s1, s6, 0x1100
	v_readlane_b32 s6, v245, 55
	v_cvt_pk_bf16_f32 v0, v0, v1
	v_cvt_pk_bf16_f32 v1, v2, v3
	v_cvt_pk_bf16_f32 v2, v4, v5
	v_cvt_pk_bf16_f32 v3, v6, v7
	v_readlane_b32 s7, v245, 56
	s_add_u32 s6, s6, s1
	ds_write_b128 v178, v[0:3] offset:45888
	s_waitcnt lgkmcnt(0)
	s_barrier
	s_addc_u32 s7, s7, s0
	s_lshl_b64 s[0:1], s[8:9], 1
	ds_read_b128 v[0:3], v173 offset:32768
	ds_read_b128 v[4:7], v173 offset:37120
	s_add_u32 s0, s6, s0
	s_addc_u32 s1, s7, s1
	v_lshl_add_u64 v[12:13], s[0:1], 0, v[92:93]
	v_lshl_add_u64 v[8:9], v[94:95], 1, v[12:13]
	s_waitcnt lgkmcnt(1)
	global_store_dwordx4 v[8:9], v[0:3], off nt
	v_lshl_add_u64 v[14:15], v[100:101], 1, v[12:13]
	s_mov_b64 s[12:13], -1
	v_add_co_u32_e32 v0, vcc, s23, v8
	s_nop 1
	v_addc_co_u32_e32 v1, vcc, 0, v9, vcc
	s_waitcnt lgkmcnt(0)
	global_store_dwordx4 v[0:1], v[4:7], off nt
	ds_read_b128 v[0:3], v173 offset:41472
	ds_read_b128 v[4:7], v173 offset:45824
	v_add_co_u32_e32 v8, vcc, s21, v8
	s_nop 1
	v_addc_co_u32_e32 v9, vcc, 0, v9, vcc
	s_waitcnt lgkmcnt(1)
	global_store_dwordx4 v[8:9], v[0:3], off nt
	ds_read_b128 v[0:3], v173 offset:50176
	v_lshl_add_u64 v[8:9], v[96:97], 1, v[12:13]
	s_waitcnt lgkmcnt(1)
	global_store_dwordx4 v[8:9], v[4:7], off nt
	v_lshl_add_u64 v[8:9], v[98:99], 1, v[12:13]
	ds_read_b128 v[4:7], v173 offset:54528
	s_waitcnt lgkmcnt(1)
	global_store_dwordx4 v[8:9], v[0:3], off nt
	ds_read_b128 v[0:3], v173 offset:58880
	ds_read_b128 v[8:11], v173 offset:63232
	s_andn2_b64 vcc, exec, s[10:11]
	s_waitcnt lgkmcnt(2)
	global_store_dwordx4 v[14:15], v[4:7], off nt
	s_nop 1
	v_lshl_add_u64 v[4:5], v[102:103], 1, v[12:13]
	s_waitcnt lgkmcnt(1)
	global_store_dwordx4 v[4:5], v[0:3], off nt
	s_nop 1
	v_lshl_add_u64 v[0:1], v[104:105], 1, v[12:13]
	s_waitcnt lgkmcnt(0)
	global_store_dwordx4 v[0:1], v[8:11], off nt
	s_cbranch_vccz .LBB0_757
	.p2alignl 6, 3212836864

; __device__ __forceinline__ u32x4 pack8(f32x4 a, f32x4 b) { u32x4 r; r.x = cvt_pk_bf16(a[0], a[1]); r.y = cvt_pk_bf16(a[2], a[3]); r.z = cvt_pk_bf16(b[0], b[1]); r.w = cvt_pk_bf16(b[2], b[3]); return r; }
; template <class Epi>
; __device__ __forceinline__ void gemm_tile(const bf16_t* __restrict__ A, const bf16_t* __restrict__ Bt, int K, int row0, int col0, const Epi& epi, char* smem,
;                                           bool prefetched, bool nvalid, int nrow0, int ncol0) {
;     ...
;     if constexpr (Epi::STAGED) {
;         bf16_t* st = (bf16_t*)(smem + 2 * TILE_B);
;         epi.to_lds(acc, st, row0, col0, wr, wc, fr, fq);
;         __syncthreads();
;         bf16_t* gbase; size_t gstride;
;         epi.dest(row0, col0, gbase, gstride);
;         const int r0 = tid >> 4, ch = (tid & 15) * 8;
; #pragma unroll
;         for (int it = 0; it < 8; ++it) { const int r = it * 16 + r0; __builtin_nontemporal_store(*(const u32x4*)(st + r * 136 + ch), (u32x4*)(gbase + (size_t)r * gstride + ch)); }
;     __device__ __forceinline__ void to_lds(f32x4 (&acc)[4][4], bf16_t* st, int row0, int col0, int wr, int wc, int fr, int fq) const {
; #pragma unroll
;         for (int m = 0; m < 4; ++m)
; #pragma unroll
;             for (int pp = 0; pp < 2; ++pp)
;                 *(u32x4*)(st + (wr * 64 + m * 16 + fr) * 136 + wc * 64 + pp * 32 + 8 * fq) = pack8(acc[m][2 * pp], acc[m][2 * pp + 1]);
.LBB0_760:
	s_ashr_i32 s8, s0, 12
	s_ashr_i32 s9, s8, 31
	s_lshl_b64 s[8:9], s[8:9], 23
	s_lshl_b64 s[2:3], s[2:3], 13
	v_readlane_b32 s1, v245, 57
	s_add_u32 s1, s1, s8
	v_readlane_b32 s8, v245, 58
	s_addc_u32 s8, s8, s9
	s_add_u32 s1, s1, s2
	v_cvt_pk_bf16_f32 v56, v56, v57
	v_cvt_pk_bf16_f32 v57, v58, v59
	v_cvt_pk_bf16_f32 v58, v60, v61
	v_cvt_pk_bf16_f32 v59, v62, v63
	v_cvt_pk_bf16_f32 v48, v48, v49
	v_cvt_pk_bf16_f32 v49, v50, v51
	v_cvt_pk_bf16_f32 v50, v52, v53
	v_cvt_pk_bf16_f32 v51, v54, v55
	v_cvt_pk_bf16_f32 v44, v44, v45
	v_cvt_pk_bf16_f32 v45, v46, v47
	v_cvt_pk_bf16_f32 v46, v40, v41
	v_cvt_pk_bf16_f32 v47, v42, v43
	v_cvt_pk_bf16_f32 v36, v36, v37
	v_cvt_pk_bf16_f32 v37, v38, v39
	v_cvt_pk_bf16_f32 v38, v32, v33
	v_cvt_pk_bf16_f32 v39, v34, v35
	v_cvt_pk_bf16_f32 v28, v28, v29
	v_cvt_pk_bf16_f32 v29, v30, v31
	v_cvt_pk_bf16_f32 v30, v24, v25
	v_cvt_pk_bf16_f32 v31, v26, v27
	v_cvt_pk_bf16_f32 v20, v20, v21
	v_cvt_pk_bf16_f32 v21, v22, v23
	v_cvt_pk_bf16_f32 v22, v16, v17
	v_cvt_pk_bf16_f32 v23, v18, v19
	v_cvt_pk_bf16_f32 v4, v4, v5
	v_cvt_pk_bf16_f32 v5, v6, v7
	v_cvt_pk_bf16_f32 v6, v8, v9
	v_cvt_pk_bf16_f32 v7, v10, v11
	v_cvt_pk_bf16_f32 v0, v0, v1
	v_cvt_pk_bf16_f32 v1, v2, v3
	v_cvt_pk_bf16_f32 v2, v12, v13
	v_cvt_pk_bf16_f32 v3, v14, v15
	s_addc_u32 s2, s8, s3
	s_and_b32 s0, s0, 0xf80
	ds_write_b128 v142, v[56:59] offset:32768
	ds_write_b128 v142, v[48:51] offset:32832
	ds_write_b128 v142, v[44:47] offset:37120
	ds_write_b128 v142, v[36:39] offset:37184
	ds_write_b128 v142, v[28:31] offset:41472
	ds_write_b128 v142, v[20:23] offset:41536
	ds_write_b128 v142, v[4:7] offset:45824
	ds_write_b128 v142, v[0:3] offset:45888
	s_waitcnt lgkmcnt(0)
	s_barrier
	s_lshl_b32 s0, s0, 1
	ds_read_b128 v[0:3], v143 offset:32768
	ds_read_b128 v[4:7], v143 offset:37120
	s_add_u32 s0, s1, s0
	s_addc_u32 s1, s2, 0
	v_lshl_add_u64 v[12:13], s[0:1], 0, v[72:73]
	v_lshl_add_u64 v[8:9], v[74:75], 1, v[12:13]
	s_waitcnt lgkmcnt(1)
	global_store_dwordx4 v[8:9], v[0:3], off nt
	ds_read_b128 v[0:3], v143 offset:41472
	v_lshl_add_u64 v[8:9], v[76:77], 1, v[12:13]
	s_waitcnt lgkmcnt(1)
	global_store_dwordx4 v[8:9], v[4:7], off nt
	ds_read_b128 v[4:7], v143 offset:45824
	v_lshl_add_u64 v[8:9], v[78:79], 1, v[12:13]
	s_waitcnt lgkmcnt(1)
	global_store_dwordx4 v[8:9], v[0:3], off nt
	ds_read_b128 v[0:3], v143 offset:50176
	v_lshl_add_u64 v[8:9], v[80:81], 1, v[12:13]
	s_waitcnt lgkmcnt(1)
	global_store_dwordx4 v[8:9], v[4:7], off nt
	v_lshl_add_u64 v[8:9], v[82:83], 1, v[12:13]
	ds_read_b128 v[4:7], v143 offset:54528
	s_waitcnt lgkmcnt(1)
	global_store_dwordx4 v[8:9], v[0:3], off nt
	ds_read_b128 v[0:3], v143 offset:58880
	ds_read_b128 v[8:11], v143 offset:63232
	v_lshl_add_u64 v[14:15], v[84:85], 1, v[12:13]
	s_waitcnt lgkmcnt(2)
	global_store_dwordx4 v[14:15], v[4:7], off nt
	s_andn2_b64 vcc, exec, s[6:7]
	s_mov_b64 s[10:11], -1
	v_lshl_add_u64 v[4:5], v[86:87], 1, v[12:13]
	s_waitcnt lgkmcnt(1)
	global_store_dwordx4 v[4:5], v[0:3], off nt
	s_nop 1
	v_lshl_add_u64 v[0:1], v[88:89], 1, v[12:13]
	s_waitcnt lgkmcnt(0)
	global_store_dwordx4 v[0:1], v[8:11], off nt
	s_cbranch_vccz .LBB0_769
	.p2alignl 6, 3212836864

;     __device__ __forceinline__ void operator()(f32x4 (&acc)[4][4], int rb, int cb, int fr, int fq) const {
;         f32x4 r[4][2][2];
; #pragma unroll
;         for (int m = 0; m < 4; ++m)
; #pragma unroll
;             for (int pp = 0; pp < 2; ++pp) {
;                 const size_t o = (size_t)(rb + m * 16 + fr) * D + cb + pp * 32 + 8 * fq;
;                 r[m][pp][0] = __builtin_nontemporal_load((const f32x4*)(res + o));
;                 r[m][pp][1] = __builtin_nontemporal_load((const f32x4*)(res + o + 4));
;             }
; #pragma unroll
;         for (int m = 0; m < 4; ++m)
; #pragma unroll
;             for (int pp = 0; pp < 2; ++pp) {
;                 const size_t o = (size_t)(rb + m * 16 + fr) * D + cb + pp * 32 + 8 * fq;
;                 *(f32x4*)(out + o) = r[m][pp][0] + acc[m][2 * pp];
;                 *(f32x4*)(out + o + 4) = r[m][pp][1] + acc[m][2 * pp + 1];
;             }
;     }
.LBB0_889:
	v_add_u32_e32 v182, s0, v73
	v_or_b32_e32 v144, s2, v148
	v_or_b32_e32 v132, 16, v182
	v_or_b32_e32 v174, 32, v182
	v_or_b32_e32 v192, 48, v182
	v_ashrrev_i32_e32 v145, 31, v144
	v_ashrrev_i32_e32 v183, 31, v182
	v_ashrrev_i32_e32 v133, 31, v132
	v_ashrrev_i32_e32 v175, 31, v174
	v_ashrrev_i32_e32 v193, 31, v192
	v_lshl_add_u64 v[190:191], v[144:145], 2, v[74:75]
	v_lshlrev_b64 v[92:93], 12, v[182:183]
	v_lshlrev_b64 v[208:209], 12, v[132:133]
	v_lshlrev_b64 v[210:211], 12, v[174:175]
	v_lshlrev_b64 v[212:213], 12, v[192:193]
	v_lshl_add_u64 v[206:207], v[190:191], 0, v[92:93]
	v_lshl_add_u64 v[170:171], v[190:191], 0, v[208:209]
	v_lshl_add_u64 v[186:187], v[190:191], 0, v[210:211]
	v_lshl_add_u64 v[202:203], v[190:191], 0, v[212:213]
	global_load_dwordx4 v[92:95], v[206:207], off nt
	global_load_dwordx4 v[96:99], v[206:207], off offset:16 nt
	global_load_dwordx4 v[100:103], v[206:207], off offset:128 nt
	global_load_dwordx4 v[104:107], v[206:207], off offset:144 nt
	global_load_dwordx4 v[132:135], v[170:171], off nt
	global_load_dwordx4 v[136:139], v[170:171], off offset:16 nt
	global_load_dwordx4 v[140:143], v[170:171], off offset:144 nt
	s_nop 0
	global_load_dwordx4 v[170:173], v[170:171], off offset:128 nt
	s_nop 0
	global_load_dwordx4 v[174:177], v[186:187], off nt
	global_load_dwordx4 v[178:181], v[186:187], off offset:16 nt
	global_load_dwordx4 v[182:185], v[186:187], off offset:144 nt
	s_nop 0
	global_load_dwordx4 v[186:189], v[186:187], off offset:128 nt
	s_nop 0
	global_load_dwordx4 v[190:193], v[202:203], off nt
	global_load_dwordx4 v[194:197], v[202:203], off offset:16 nt
	global_load_dwordx4 v[198:201], v[202:203], off offset:128 nt
	s_nop 0
	global_load_dwordx4 v[202:205], v[202:203], off offset:144 nt
	v_or_b32_e32 v144, v144, v72
	v_lshlrev_b64 v[144:145], 2, v[144:145]
	v_lshl_add_u64 v[208:209], s[54:55], 0, v[208:209]
	v_lshl_add_u64 v[210:211], s[54:55], 0, v[210:211]
	v_lshl_add_u64 v[212:213], s[54:55], 0, v[212:213]
	v_lshl_add_u64 v[208:209], v[208:209], 0, v[144:145]
	v_lshl_add_u64 v[210:211], v[210:211], 0, v[144:145]
	v_lshl_add_u64 v[144:145], v[212:213], 0, v[144:145]
	s_andn2_b64 vcc, exec, s[6:7]
	s_mov_b64 s[10:11], -1
	s_waitcnt vmcnt(0)
	v_pk_add_f32 v[54:55], v[54:55], v[94:95]
	v_pk_add_f32 v[52:53], v[52:53], v[92:93]
	v_pk_add_f32 v[58:59], v[58:59], v[98:99]
	v_pk_add_f32 v[46:47], v[46:47], v[134:135]
	v_pk_add_f32 v[44:45], v[44:45], v[132:133]
	v_pk_add_f32 v[56:57], v[56:57], v[96:97]
	v_pk_add_f32 v[62:63], v[62:63], v[102:103]
	v_pk_add_f32 v[60:61], v[60:61], v[100:101]
	v_pk_add_f32 v[2:3], v[2:3], v[204:205]
	v_pk_add_f32 v[0:1], v[0:1], v[202:203]
	v_pk_add_f32 v[50:51], v[50:51], v[106:107]
	v_pk_add_f32 v[48:49], v[48:49], v[104:105]
	global_store_dwordx4 v[206:207], v[52:55], off
	global_store_dwordx4 v[206:207], v[56:59], off offset:16
	global_store_dwordx4 v[206:207], v[60:63], off offset:128
	global_store_dwordx4 v[206:207], v[48:51], off offset:144
	v_pk_add_f32 v[42:43], v[42:43], v[138:139]
	v_pk_add_f32 v[40:41], v[40:41], v[136:137]
	v_pk_add_f32 v[34:35], v[34:35], v[172:173]
	v_pk_add_f32 v[32:33], v[32:33], v[170:171]
	v_pk_add_f32 v[26:27], v[26:27], v[142:143]
	v_pk_add_f32 v[24:25], v[24:25], v[140:141]
	v_pk_add_f32 v[38:39], v[38:39], v[176:177]
	v_pk_add_f32 v[36:37], v[36:37], v[174:175]
	v_pk_add_f32 v[30:31], v[30:31], v[180:181]
	v_pk_add_f32 v[28:29], v[28:29], v[178:179]
	v_pk_add_f32 v[22:23], v[22:23], v[188:189]
	v_pk_add_f32 v[20:21], v[20:21], v[186:187]
	v_pk_add_f32 v[18:19], v[18:19], v[184:185]
	v_pk_add_f32 v[16:17], v[16:17], v[182:183]
	v_pk_add_f32 v[14:15], v[14:15], v[192:193]
	v_pk_add_f32 v[12:13], v[12:13], v[190:191]
	v_pk_add_f32 v[10:11], v[10:11], v[196:197]
	v_pk_add_f32 v[8:9], v[8:9], v[194:195]
	v_pk_add_f32 v[6:7], v[6:7], v[200:201]
	v_pk_add_f32 v[4:5], v[4:5], v[198:199]
	global_store_dwordx4 v[208:209], v[44:47], off
	global_store_dwordx4 v[208:209], v[40:43], off offset:16
	global_store_dwordx4 v[208:209], v[32:35], off offset:128
	global_store_dwordx4 v[208:209], v[24:27], off offset:144
	global_store_dwordx4 v[210:211], v[36:39], off
	global_store_dwordx4 v[210:211], v[28:31], off offset:16
	global_store_dwordx4 v[210:211], v[20:23], off offset:128
	global_store_dwordx4 v[210:211], v[16:19], off offset:144
	global_store_dwordx4 v[144:145], v[12:15], off
	global_store_dwordx4 v[144:145], v[8:11], off offset:16
	global_store_dwordx4 v[144:145], v[4:7], off offset:128
	global_store_dwordx4 v[144:145], v[0:3], off offset:144
	s_cbranch_vccz .LBB0_898
	.p2alignl 6, 3212836864

; __device__ __forceinline__ u32x4 pack8(f32x4 a, f32x4 b) { u32x4 r; r.x = cvt_pk_bf16(a[0], a[1]); r.y = cvt_pk_bf16(a[2], a[3]); r.z = cvt_pk_bf16(b[0], b[1]); r.w = cvt_pk_bf16(b[2], b[3]); return r; }
;     __device__ __forceinline__ void to_lds(f32x4 (&acc)[4][4], bf16_t* st, int row0, int col0, int wr, int wc, int fr, int fq) const {
; #pragma unroll
;         for (int m = 0; m < 4; ++m)
; #pragma unroll
;             for (int pp = 0; pp < 2; ++pp) {
;                 f32x4 v0 = acc[m][2 * pp], v1 = acc[m][2 * pp + 1];
; #pragma unroll
;                 for (int j = 0; j < 4; ++j) { const float u0 = fmaxf(v0[j], 0.f), u1 = fmaxf(v1[j], 0.f); v0[j] = u0 * u0; v1[j] = u1 * u1; }
;                 *(u32x4*)(st + (wr * 64 + m * 16 + fr) * 136 + wc * 64 + pp * 32 + 8 * fq) = pack8(v0, v1);
;             }
;     }
.LBB0_992:
	v_max_f32_e32 v48, v48, v48
	v_max_f32_e32 v52, v52, v52
	v_max_f32_e32 v49, v49, v49
	v_max_f32_e32 v53, v53, v53
	v_max_f32_e32 v50, v50, v50
	v_max_f32_e32 v54, v54, v54
	v_max_f32_e32 v51, v51, v51
	v_max_f32_e32 v55, v55, v55
	v_max_f32_e32 v48, 0, v48
	v_max_f32_e32 v52, 0, v52
	v_max_f32_e32 v49, 0, v49
	v_max_f32_e32 v53, 0, v53
	v_max_f32_e32 v50, 0, v50
	v_max_f32_e32 v54, 0, v54
	v_max_f32_e32 v51, 0, v51
	v_max_f32_e32 v55, 0, v55
	v_pk_mul_f32 v[48:49], v[48:49], v[48:49]
	v_pk_mul_f32 v[52:53], v[52:53], v[52:53]
	v_pk_mul_f32 v[50:51], v[50:51], v[50:51]
	v_pk_mul_f32 v[54:55], v[54:55], v[54:55]
	v_max_f32_e32 v40, v40, v40
	v_max_f32_e32 v41, v41, v41
	v_cvt_pk_bf16_f32 v48, v48, v49
	v_cvt_pk_bf16_f32 v49, v50, v51
	v_cvt_pk_bf16_f32 v50, v52, v53
	v_cvt_pk_bf16_f32 v51, v54, v55
	v_max_f32_e32 v40, 0, v40
	v_max_f32_e32 v41, 0, v41
	ds_write_b128 v141, v[48:51] offset:32832
	v_pk_mul_f32 v[48:49], v[40:41], v[40:41]
	v_max_f32_e32 v41, v42, v42
	v_max_f32_e32 v44, v44, v44
	v_max_f32_e32 v45, v45, v45
	v_max_f32_e32 v40, v46, v46
	v_max_f32_e32 v42, 0, v41
	v_max_f32_e32 v41, v47, v47
	v_max_f32_e32 v43, v43, v43
	v_max_f32_e32 v44, 0, v44
	v_max_f32_e32 v45, 0, v45
	v_max_f32_e32 v40, 0, v40
	v_max_f32_e32 v41, 0, v41
	v_max_f32_e32 v43, 0, v43
	v_pk_mul_f32 v[44:45], v[44:45], v[44:45]
	v_pk_mul_f32 v[46:47], v[40:41], v[40:41]
	v_pk_mul_f32 v[50:51], v[42:43], v[42:43]
	v_max_f32_e32 v32, v32, v32
	v_max_f32_e32 v33, v33, v33
	v_cvt_pk_bf16_f32 v40, v44, v45
	v_cvt_pk_bf16_f32 v41, v46, v47
	v_cvt_pk_bf16_f32 v42, v48, v49
	v_cvt_pk_bf16_f32 v43, v50, v51
	v_max_f32_e32 v32, 0, v32
	v_max_f32_e32 v33, 0, v33
	ds_write_b128 v141, v[40:43] offset:37120
	v_pk_mul_f32 v[40:41], v[32:33], v[32:33]
	v_max_f32_e32 v33, v34, v34
	v_max_f32_e32 v36, v36, v36
	v_max_f32_e32 v37, v37, v37
	v_max_f32_e32 v32, v38, v38
	v_max_f32_e32 v34, 0, v33
	v_max_f32_e32 v33, v39, v39
	v_max_f32_e32 v35, v35, v35
	v_max_f32_e32 v36, 0, v36
	v_max_f32_e32 v37, 0, v37
	v_max_f32_e32 v32, 0, v32
	v_max_f32_e32 v33, 0, v33
	v_max_f32_e32 v35, 0, v35
	v_pk_mul_f32 v[36:37], v[36:37], v[36:37]
	v_pk_mul_f32 v[38:39], v[32:33], v[32:33]
	v_pk_mul_f32 v[42:43], v[34:35], v[34:35]
	v_max_f32_e32 v24, v24, v24
	v_max_f32_e32 v25, v25, v25
	v_cvt_pk_bf16_f32 v32, v36, v37
	v_cvt_pk_bf16_f32 v33, v38, v39
	v_cvt_pk_bf16_f32 v34, v40, v41
	v_cvt_pk_bf16_f32 v35, v42, v43
	v_max_f32_e32 v24, 0, v24
	v_max_f32_e32 v25, 0, v25
	ds_write_b128 v141, v[32:35] offset:37184
	v_pk_mul_f32 v[32:33], v[24:25], v[24:25]
	v_max_f32_e32 v25, v26, v26
	v_max_f32_e32 v28, v28, v28
	v_max_f32_e32 v29, v29, v29
	v_max_f32_e32 v24, v30, v30
	v_max_f32_e32 v26, 0, v25
	v_max_f32_e32 v25, v31, v31
	v_max_f32_e32 v27, v27, v27
	v_max_f32_e32 v28, 0, v28
	v_max_f32_e32 v29, 0, v29
	v_max_f32_e32 v24, 0, v24
	v_max_f32_e32 v25, 0, v25
	v_max_f32_e32 v27, 0, v27
	v_pk_mul_f32 v[28:29], v[28:29], v[28:29]
	v_pk_mul_f32 v[30:31], v[24:25], v[24:25]
	v_pk_mul_f32 v[34:35], v[26:27], v[26:27]
	v_max_f32_e32 v16, v16, v16
	v_max_f32_e32 v17, v17, v17
	v_cvt_pk_bf16_f32 v24, v28, v29
	v_cvt_pk_bf16_f32 v25, v30, v31
	v_cvt_pk_bf16_f32 v26, v32, v33
	v_cvt_pk_bf16_f32 v27, v34, v35
	v_max_f32_e32 v16, 0, v16
	v_max_f32_e32 v17, 0, v17
	ds_write_b128 v141, v[24:27] offset:41472
	v_pk_mul_f32 v[24:25], v[16:17], v[16:17]
	v_max_f32_e32 v17, v18, v18
	v_max_f32_e32 v56, v56, v56
	v_max_f32_e32 v60, v60, v60
	v_max_f32_e32 v57, v57, v57
	v_max_f32_e32 v61, v61, v61
	v_max_f32_e32 v58, v58, v58
	v_max_f32_e32 v62, v62, v62
	v_max_f32_e32 v59, v59, v59
	v_max_f32_e32 v63, v63, v63
	v_max_f32_e32 v20, v20, v20
	v_max_f32_e32 v21, v21, v21
	v_max_f32_e32 v16, v22, v22
	v_max_f32_e32 v18, 0, v17
	v_max_f32_e32 v17, v23, v23
	v_max_f32_e32 v19, v19, v19
	v_max_f32_e32 v8, v8, v8
	v_max_f32_e32 v12, v12, v12
	v_max_f32_e32 v9, v9, v9
	v_max_f32_e32 v13, v13, v13
	v_max_f32_e32 v10, v10, v10
	v_max_f32_e32 v14, v14, v14
	v_max_f32_e32 v11, v11, v11
	v_max_f32_e32 v15, v15, v15
	v_max_f32_e32 v0, v0, v0
	v_max_f32_e32 v4, v4, v4
	v_max_f32_e32 v1, v1, v1
	v_max_f32_e32 v5, v5, v5
	v_max_f32_e32 v2, v2, v2
	v_max_f32_e32 v6, v6, v6
	v_max_f32_e32 v3, v3, v3
	v_max_f32_e32 v7, v7, v7
	v_max_f32_e32 v56, 0, v56
	v_max_f32_e32 v60, 0, v60
	v_max_f32_e32 v57, 0, v57
	v_max_f32_e32 v61, 0, v61
	v_max_f32_e32 v58, 0, v58
	v_max_f32_e32 v62, 0, v62
	v_max_f32_e32 v59, 0, v59
	v_max_f32_e32 v63, 0, v63
	v_max_f32_e32 v20, 0, v20
	v_max_f32_e32 v21, 0, v21
	v_max_f32_e32 v16, 0, v16
	v_max_f32_e32 v17, 0, v17
	v_max_f32_e32 v19, 0, v19
	v_max_f32_e32 v8, 0, v8
	v_max_f32_e32 v12, 0, v12
	v_max_f32_e32 v9, 0, v9
	v_max_f32_e32 v13, 0, v13
	v_max_f32_e32 v10, 0, v10
	v_max_f32_e32 v14, 0, v14
	v_max_f32_e32 v11, 0, v11
	v_max_f32_e32 v15, 0, v15
	v_max_f32_e32 v0, 0, v0
	v_max_f32_e32 v4, 0, v4
	v_max_f32_e32 v1, 0, v1
	v_max_f32_e32 v5, 0, v5
	v_max_f32_e32 v2, 0, v2
	v_max_f32_e32 v6, 0, v6
	v_max_f32_e32 v3, 0, v3
	v_max_f32_e32 v7, 0, v7
	v_pk_mul_f32 v[56:57], v[56:57], v[56:57]
	v_pk_mul_f32 v[60:61], v[60:61], v[60:61]
	v_pk_mul_f32 v[58:59], v[58:59], v[58:59]
	v_pk_mul_f32 v[62:63], v[62:63], v[62:63]
	v_pk_mul_f32 v[20:21], v[20:21], v[20:21]
	v_pk_mul_f32 v[22:23], v[16:17], v[16:17]
	v_pk_mul_f32 v[26:27], v[18:19], v[18:19]
	v_pk_mul_f32 v[8:9], v[8:9], v[8:9]
	v_pk_mul_f32 v[12:13], v[12:13], v[12:13]
	v_pk_mul_f32 v[10:11], v[10:11], v[10:11]
	v_pk_mul_f32 v[14:15], v[14:15], v[14:15]
	v_pk_mul_f32 v[0:1], v[0:1], v[0:1]
	v_pk_mul_f32 v[4:5], v[4:5], v[4:5]
	v_pk_mul_f32 v[2:3], v[2:3], v[2:3]
	v_pk_mul_f32 v[6:7], v[6:7], v[6:7]
	s_lshl_b64 s[0:1], s[0:1], 13
	v_readlane_b32 s8, v245, 55
	v_cvt_pk_bf16_f32 v56, v56, v57
	v_cvt_pk_bf16_f32 v57, v58, v59
	v_cvt_pk_bf16_f32 v58, v60, v61
	v_cvt_pk_bf16_f32 v59, v62, v63
	v_cvt_pk_bf16_f32 v16, v20, v21
	v_cvt_pk_bf16_f32 v17, v22, v23
	v_cvt_pk_bf16_f32 v18, v24, v25
	v_cvt_pk_bf16_f32 v19, v26, v27
	v_cvt_pk_bf16_f32 v8, v8, v9
	v_cvt_pk_bf16_f32 v9, v10, v11
	v_cvt_pk_bf16_f32 v10, v12, v13
	v_cvt_pk_bf16_f32 v11, v14, v15
	v_cvt_pk_bf16_f32 v0, v0, v1
	v_cvt_pk_bf16_f32 v1, v2, v3
	v_cvt_pk_bf16_f32 v2, v4, v5
	v_cvt_pk_bf16_f32 v3, v6, v7
	v_readlane_b32 s9, v245, 56
	s_add_u32 s8, s8, s0
	ds_write_b128 v141, v[56:59] offset:32768
	ds_write_b128 v141, v[16:19] offset:41536
	ds_write_b128 v141, v[8:11] offset:45824
	ds_write_b128 v141, v[0:3] offset:45888
	s_waitcnt lgkmcnt(0)
	s_barrier
; template <class Epi>
; __device__ __forceinline__ void gemm_tile(const bf16_t* __restrict__ A, const bf16_t* __restrict__ Bt, int K, int row0, int col0, const Epi& epi, char* smem,
;                                           bool prefetched, bool nvalid, int nrow0, int ncol0) {
;     ...
;         __syncthreads();
;         bf16_t* gbase; size_t gstride;
;         epi.dest(row0, col0, gbase, gstride);
;         const int r0 = tid >> 4, ch = (tid & 15) * 8;
; #pragma unroll
;         for (int it = 0; it < 8; ++it) { const int r = it * 16 + r0; __builtin_nontemporal_store(*(const u32x4*)(st + r * 136 + ch), (u32x4*)(gbase + (size_t)r * gstride + ch)); }
	s_addc_u32 s9, s9, s1
	s_lshl_b64 s[0:1], s[2:3], 1
	ds_read_b128 v[0:3], v142 offset:32768
	ds_read_b128 v[4:7], v142 offset:37120
	s_add_u32 s0, s8, s0
	s_addc_u32 s1, s9, s1
	v_lshl_add_u64 v[12:13], s[0:1], 0, v[72:73]
	v_lshl_add_u64 v[8:9], v[74:75], 1, v[12:13]
	s_waitcnt lgkmcnt(1)
	global_store_dwordx4 v[8:9], v[0:3], off nt
	ds_read_b128 v[0:3], v142 offset:41472
	v_lshl_add_u64 v[8:9], v[76:77], 1, v[12:13]
	s_waitcnt lgkmcnt(1)
	global_store_dwordx4 v[8:9], v[4:7], off nt
	ds_read_b128 v[4:7], v142 offset:45824
	v_lshl_add_u64 v[8:9], v[78:79], 1, v[12:13]
	s_waitcnt lgkmcnt(1)
	global_store_dwordx4 v[8:9], v[0:3], off nt
	ds_read_b128 v[0:3], v142 offset:50176
	v_lshl_add_u64 v[8:9], v[80:81], 1, v[12:13]
	s_waitcnt lgkmcnt(1)
	global_store_dwordx4 v[8:9], v[4:7], off nt
	v_lshl_add_u64 v[8:9], v[82:83], 1, v[12:13]
	ds_read_b128 v[4:7], v142 offset:54528
	s_waitcnt lgkmcnt(1)
	global_store_dwordx4 v[8:9], v[0:3], off nt
	ds_read_b128 v[0:3], v142 offset:58880
	ds_read_b128 v[8:11], v142 offset:63232
	v_lshl_add_u64 v[14:15], v[84:85], 1, v[12:13]
	s_waitcnt lgkmcnt(2)
	global_store_dwordx4 v[14:15], v[4:7], off nt
	s_andn2_b64 vcc, exec, s[6:7]
	s_mov_b64 s[10:11], -1
	v_lshl_add_u64 v[4:5], v[86:87], 1, v[12:13]
	s_waitcnt lgkmcnt(1)
	global_store_dwordx4 v[4:5], v[0:3], off nt
	s_nop 1
	v_lshl_add_u64 v[0:1], v[88:89], 1, v[12:13]
	s_waitcnt lgkmcnt(0)
	global_store_dwordx4 v[0:1], v[8:11], off nt
	s_cbranch_vccz .LBB0_1001
	.p2alignl 6, 3212836864

;     __device__ __forceinline__ void operator()(f32x4 (&acc)[4][4], int rb, int cb, int fr, int fq) const {
;         f32x4 r[4][2][2];
; #pragma unroll
;         for (int m = 0; m < 4; ++m)
; #pragma unroll
;             for (int pp = 0; pp < 2; ++pp) {
;                 const size_t o = (size_t)(rb + m * 16 + fr) * D + cb + pp * 32 + 8 * fq;
;                 r[m][pp][0] = __builtin_nontemporal_load((const f32x4*)(res + o));
;                 r[m][pp][1] = __builtin_nontemporal_load((const f32x4*)(res + o + 4));
;             }
; #pragma unroll
;         for (int m = 0; m < 4; ++m)
; #pragma unroll
;             for (int pp = 0; pp < 2; ++pp) {
;                 const size_t o = (size_t)(rb + m * 16 + fr) * D + cb + pp * 32 + 8 * fq;
;                 *(f32x4*)(out + o) = r[m][pp][0] + acc[m][2 * pp];
;                 *(f32x4*)(out + o + 4) = r[m][pp][1] + acc[m][2 * pp + 1];
;             }
;     }
.LBB0_1048:
	v_add_u32_e32 v158, s0, v73
	v_or_b32_e32 v144, s2, v148
	v_or_b32_e32 v128, 16, v158
	v_or_b32_e32 v150, 32, v158
	v_or_b32_e32 v174, 48, v158
	v_ashrrev_i32_e32 v145, 31, v144
	v_ashrrev_i32_e32 v159, 31, v158
	v_ashrrev_i32_e32 v129, 31, v128
	v_ashrrev_i32_e32 v151, 31, v150
	v_ashrrev_i32_e32 v175, 31, v174
	v_lshl_add_u64 v[172:173], v[144:145], 2, v[74:75]
	v_lshlrev_b64 v[92:93], 12, v[158:159]
	v_lshlrev_b64 v[190:191], 12, v[128:129]
	v_lshlrev_b64 v[192:193], 12, v[150:151]
	v_lshlrev_b64 v[194:195], 12, v[174:175]
	v_lshl_add_u64 v[188:189], v[172:173], 0, v[92:93]
	v_lshl_add_u64 v[140:141], v[172:173], 0, v[190:191]
	v_lshl_add_u64 v[168:169], v[172:173], 0, v[192:193]
	v_lshl_add_u64 v[184:185], v[172:173], 0, v[194:195]
	global_load_dwordx4 v[92:95], v[188:189], off nt
	global_load_dwordx4 v[96:99], v[188:189], off offset:16 nt
	global_load_dwordx4 v[100:103], v[188:189], off offset:128 nt
	global_load_dwordx4 v[104:107], v[188:189], off offset:144 nt
	global_load_dwordx4 v[128:131], v[140:141], off nt
	global_load_dwordx4 v[132:135], v[140:141], off offset:16 nt
	global_load_dwordx4 v[136:139], v[140:141], off offset:144 nt
	s_nop 0
	global_load_dwordx4 v[140:143], v[140:141], off offset:128 nt
	s_nop 0
	global_load_dwordx4 v[150:153], v[168:169], off nt
	global_load_dwordx4 v[154:157], v[168:169], off offset:16 nt
	global_load_dwordx4 v[158:161], v[168:169], off offset:144 nt
	s_nop 0
	global_load_dwordx4 v[168:171], v[168:169], off offset:128 nt
	s_nop 0
	global_load_dwordx4 v[172:175], v[184:185], off nt
	global_load_dwordx4 v[176:179], v[184:185], off offset:16 nt
	global_load_dwordx4 v[180:183], v[184:185], off offset:128 nt
	s_nop 0
	global_load_dwordx4 v[184:187], v[184:185], off offset:144 nt
	v_or_b32_e32 v144, v144, v72
	v_lshlrev_b64 v[144:145], 2, v[144:145]
	v_lshl_add_u64 v[190:191], s[54:55], 0, v[190:191]
	v_lshl_add_u64 v[192:193], s[54:55], 0, v[192:193]
	v_lshl_add_u64 v[194:195], s[54:55], 0, v[194:195]
	v_lshl_add_u64 v[190:191], v[190:191], 0, v[144:145]
	v_lshl_add_u64 v[192:193], v[192:193], 0, v[144:145]
	v_lshl_add_u64 v[144:145], v[194:195], 0, v[144:145]
	s_andn2_b64 vcc, exec, s[4:5]
	s_mov_b64 s[8:9], -1
	s_waitcnt vmcnt(0)
	v_pk_add_f32 v[54:55], v[54:55], v[94:95]
	v_pk_add_f32 v[52:53], v[52:53], v[92:93]
	v_pk_add_f32 v[58:59], v[58:59], v[98:99]
	v_pk_add_f32 v[46:47], v[46:47], v[130:131]
	v_pk_add_f32 v[44:45], v[44:45], v[128:129]
	v_pk_add_f32 v[56:57], v[56:57], v[96:97]
	v_pk_add_f32 v[62:63], v[62:63], v[102:103]
	v_pk_add_f32 v[60:61], v[60:61], v[100:101]
	v_pk_add_f32 v[2:3], v[2:3], v[186:187]
	v_pk_add_f32 v[0:1], v[0:1], v[184:185]
	v_pk_add_f32 v[50:51], v[50:51], v[106:107]
	v_pk_add_f32 v[48:49], v[48:49], v[104:105]
	global_store_dwordx4 v[188:189], v[52:55], off
	global_store_dwordx4 v[188:189], v[56:59], off offset:16
	global_store_dwordx4 v[188:189], v[60:63], off offset:128
	global_store_dwordx4 v[188:189], v[48:51], off offset:144
	v_pk_add_f32 v[42:43], v[42:43], v[134:135]
	v_pk_add_f32 v[40:41], v[40:41], v[132:133]
	v_pk_add_f32 v[34:35], v[34:35], v[142:143]
	v_pk_add_f32 v[32:33], v[32:33], v[140:141]
	v_pk_add_f32 v[26:27], v[26:27], v[138:139]
	v_pk_add_f32 v[24:25], v[24:25], v[136:137]
	v_pk_add_f32 v[38:39], v[38:39], v[152:153]
	v_pk_add_f32 v[36:37], v[36:37], v[150:151]
	v_pk_add_f32 v[30:31], v[30:31], v[156:157]
	v_pk_add_f32 v[28:29], v[28:29], v[154:155]
	v_pk_add_f32 v[22:23], v[22:23], v[170:171]
	v_pk_add_f32 v[20:21], v[20:21], v[168:169]
	v_pk_add_f32 v[18:19], v[18:19], v[160:161]
	v_pk_add_f32 v[16:17], v[16:17], v[158:159]
	v_pk_add_f32 v[14:15], v[14:15], v[174:175]
	v_pk_add_f32 v[12:13], v[12:13], v[172:173]
	v_pk_add_f32 v[10:11], v[10:11], v[178:179]
	v_pk_add_f32 v[8:9], v[8:9], v[176:177]
	v_pk_add_f32 v[6:7], v[6:7], v[182:183]
	v_pk_add_f32 v[4:5], v[4:5], v[180:181]
	global_store_dwordx4 v[190:191], v[44:47], off
	global_store_dwordx4 v[190:191], v[40:43], off offset:16
	global_store_dwordx4 v[190:191], v[32:35], off offset:128
	global_store_dwordx4 v[190:191], v[24:27], off offset:144
	global_store_dwordx4 v[192:193], v[36:39], off
	global_store_dwordx4 v[192:193], v[28:31], off offset:16
	global_store_dwordx4 v[192:193], v[20:23], off offset:128
	global_store_dwordx4 v[192:193], v[16:19], off offset:144
	global_store_dwordx4 v[144:145], v[12:15], off
	global_store_dwordx4 v[144:145], v[8:11], off offset:16
	global_store_dwordx4 v[144:145], v[4:7], off offset:128
	global_store_dwordx4 v[144:145], v[0:3], off offset:144
	s_cbranch_vccz .LBB0_1057
	.p2alignl 6, 3212836864
